# skip L2 writeback at XCD-local barriers B4 B5 B8 B9 (runtime-verified blockIdx%8 -> XCD grouping), sample-row stores write-through
# speedup vs baseline: 1.0057x; 1.0057x over previous
; #define LAS __attribute__((address_space(3)))
; __device__ __forceinline__ unsigned xb_add(unsigned* p, unsigned v) { return __hip_atomic_fetch_add(p, v, __ATOMIC_RELAXED, __HIP_MEMORY_SCOPE_AGENT); }
; __device__ __forceinline__ unsigned xb_xcc_id() { return (unsigned)__builtin_amdgcn_s_getreg((3 << 11) | 20) & 0xFu; }
; __device__ __forceinline__ XcdBarrier xcd_barrier_post(unsigned* bar, volatile LAS unsigned* st) {
;     XcdBarrier b; b.bar = bar; b.x = xb_xcc_id(); b.st = st;
;     if (threadIdx.x == 0) (void)xb_add(&bar[XB_XCNT(b.x)], 1u);
;     return b;
; }
; __global__ void __launch_bounds__(512, 2) fwd_megakernel(Params p) {
;     ...
;     { volatile LAS unsigned* st0 = (volatile LAS unsigned*)(F.lds + RING_BYTES + 12288); if (F.tid < 4) st0[F.tid] = 0u; }
;     __syncthreads();
;     const XcdBarrier xbar = xcd_barrier_post((unsigned*)ws, (volatile LAS unsigned*)(F.lds + RING_BYTES + 12288));
.LBB0_2:
	s_load_dword s3, s[0:1], 0x148
	s_load_dwordx16 s[44:59], s[0:1], 0x100
	v_and_b32_e32 v202, 0x3ff, v0
	v_cmp_gt_u32_e32 vcc, 4, v202
	s_waitcnt lgkmcnt(0)
	v_writelane_b32 v254, s3, 2
	s_and_saveexec_b64 s[4:5], vcc
	v_lshl_add_u32 v1, v202, 2, 0
	v_add_u32_e32 v1, 0x23000, v1
	v_mov_b32_e32 v2, 0
	ds_write_b32 v1, v2
	s_or_b64 exec, exec, s[4:5]
	s_load_dwordx16 s[4:19], s[0:1], 0xc0
	s_waitcnt lgkmcnt(0)
	s_barrier
	s_getreg_b32 s3, hwreg(HW_REG_XCC_ID, 0, 4)
	v_writelane_b32 v254, s4, 3
	s_and_b32 s3, s3, 15
	s_nop 0
	v_writelane_b32 v254, s5, 4
	v_writelane_b32 v254, s6, 5
	v_writelane_b32 v254, s7, 6
	v_writelane_b32 v254, s8, 7
	v_writelane_b32 v254, s9, 8
	v_writelane_b32 v254, s10, 9
	v_writelane_b32 v254, s11, 10
	v_writelane_b32 v254, s12, 11
	v_writelane_b32 v254, s13, 12
	v_writelane_b32 v254, s14, 13
	v_writelane_b32 v254, s15, 14
	v_writelane_b32 v254, s16, 15
	v_writelane_b32 v254, s17, 16
	v_writelane_b32 v254, s18, 17
	v_writelane_b32 v254, s19, 18
	v_writelane_b32 v254, s3, 19
	v_cmp_eq_u32_e64 s[6:7], 0, v202
	s_mov_b64 s[4:5], exec
	s_nop 0
	v_writelane_b32 v254, s6, 20
	s_nop 1
	v_writelane_b32 v254, s7, 21
	s_and_b64 s[6:7], s[4:5], s[6:7]
	s_mov_b64 exec, s[6:7]
	s_cbranch_execz .LBB0_7
	s_mov_b64 s[6:7], exec
	v_mbcnt_lo_u32_b32 v1, s6, 0
	v_mbcnt_hi_u32_b32 v1, s7, v1
	v_cmp_eq_u32_e32 vcc, 0, v1
	s_and_b64 s[8:9], exec, vcc
	s_mov_b64 exec, s[8:9]
	s_cbranch_execz .LBB0_7
	v_readlane_b32 s3, v254, 19
	s_lshl_b32 s3, s3, 8
	s_bcnt1_i32_b64 s6, s[6:7]
	v_mov_b32_e32 v1, s3
	v_mov_b32_e32 v2, s6
	global_atomic_add v1, v2, s[58:59] offset:1024
	s_lshr_b32 s3, s3, 8
	s_lshl_b32 s3, 1, s3
	s_and_b32 s6, s2, 7
	s_lshl_b32 s6, s6, 2
	s_addk_i32 s6, 0x3700
	v_mov_b32_e32 v3, s6
	v_mov_b32_e32 v4, s3
	global_atomic_or v3, v4, s[58:59]

; __device__ __forceinline__ unsigned xb_ld(unsigned* p)              { return __hip_atomic_load(p, __ATOMIC_RELAXED, __HIP_MEMORY_SCOPE_AGENT); }
; __device__ __forceinline__ unsigned xb_add(unsigned* p, unsigned v) { return __hip_atomic_fetch_add(p, v, __ATOMIC_RELAXED, __HIP_MEMORY_SCOPE_AGENT); }
; #define XB_SPIN(cond, bar) do { unsigned _sp = 0; while (cond) { __builtin_amdgcn_s_sleep(1); \
;     if ((++_sp & 255u) == 0u) { if (xb_ld(&(bar)[XB_TMO])) break; if (_sp > XB_SPIN_CAP) { atomicAdd(&(bar)[XB_TMO], 1u); break; } } } } while (0)
; __device__ __forceinline__ void xcd_barrier(const XcdBarrier& b) {
;     asm volatile("s_waitcnt vmcnt(0)" ::: "memory");
;     __syncthreads();
;     if (threadIdx.x == 0) {
;         unsigned* bar = b.bar;
;         __builtin_amdgcn_s_waitcnt(0);
;         unsigned nloc = b.st[0], nx = b.st[1];
;         if (nloc == 0u) { xcd_barrier_complete(bar, b.x, nloc, nx); b.st[0] = nloc; b.st[1] = nx; }
;         const unsigned old = xb_add(&bar[XB_XSUB(b.x)], 1u);
;         const unsigned gen = old / nloc;
;         if (old + 1u == (gen + 1u) * nloc) {
;             __builtin_amdgcn_fence(__ATOMIC_RELEASE, "agent");
;             asm volatile("s_waitcnt vmcnt(0)" ::: "memory");
;             const unsigned og = xb_add(&bar[XB_TOP], 1u);
;             const unsigned tg = og / nx;
;             if (og + 1u == (tg + 1u) * nx) xb_add(&bar[XB_TOPGEN], 1u);
;             else XB_SPIN(xb_ld(&bar[XB_TOPGEN]) == tg, bar);
;             __builtin_amdgcn_fence(__ATOMIC_ACQUIRE, "agent");
;             xb_add(&bar[XB_XGEN(b.x)], 1u);
;             asm volatile("s_waitcnt vmcnt(0)" ::: "memory");
;         } else {
;             XB_SPIN(xb_ld(&bar[XB_XGEN(b.x)]) == gen, bar);
.LBB0_468:
	s_mov_b64 s[6:7], exec
	v_readlane_b32 s3, v254, 19
	s_lshl_b32 s3, s3, 8
	v_mbcnt_lo_u32_b32 v1, s6, 0
	s_add_u32 s4, s58, s3
	v_mbcnt_hi_u32_b32 v1, s7, v1
	s_addc_u32 s5, s59, 0
	v_cmp_eq_u32_e32 vcc, 0, v1
	s_and_saveexec_b64 s[8:9], vcc
	s_cbranch_execz .LBB0_470
	s_bcnt1_i32_b64 s3, s[6:7]
	v_mov_b32_e32 v3, 0x1000
	v_mov_b32_e32 v4, s3
	global_atomic_add v3, v3, v4, s[4:5] offset:1024 sc0
	s_and_b32 s3, s2, 7
	s_lshl_b32 s3, s3, 2
	s_addk_i32 s3, 0x3700
	v_mov_b32_e32 v5, s3
	global_load_dword v5, v5, s[58:59] sc0 sc1
.LBB0_470:
	s_or_b64 exec, exec, s[8:9]
	v_cvt_f32_u32_e32 v4, v2
	s_waitcnt vmcnt(0)
	v_readfirstlane_b32 s6, v5
	v_readlane_b32 s7, v254, 19
	s_lshl_b32 s7, 1, s7
	s_cmp_eq_u32 s6, s7
	s_cbranch_scc1 .Lxgrp_ok
	v_mov_b32_e32 v5, 0x3780
	global_store_dword v5, v5, s[58:59] sc0 sc1
.Lxgrp_ok:
	v_readfirstlane_b32 s3, v3
	v_sub_u32_e32 v3, 0, v2
	v_rcp_iflag_f32_e32 v4, v4
	v_add_u32_e32 v5, s3, v1
	v_mul_f32_e32 v4, 0x4f7ffffe, v4
	v_cvt_u32_f32_e32 v4, v4
	v_mul_lo_u32 v1, v3, v4
	v_mul_hi_u32 v1, v4, v1
	v_add_u32_e32 v1, v4, v1
	v_mul_hi_u32 v1, v5, v1
	v_mul_lo_u32 v3, v1, v2
	v_sub_u32_e32 v3, v5, v3
	v_add_u32_e32 v4, 1, v1
	v_cmp_ge_u32_e32 vcc, v3, v2
	s_nop 1
	v_cndmask_b32_e32 v1, v1, v4, vcc
	v_sub_u32_e32 v4, v3, v2
	v_cndmask_b32_e32 v3, v3, v4, vcc
	v_add_u32_e32 v4, 1, v1
	v_cmp_ge_u32_e32 vcc, v3, v2
	v_add_u32_e32 v3, 1, v5
	s_nop 0
	v_cndmask_b32_e32 v1, v1, v4, vcc
	v_mul_lo_u32 v4, v2, v1
	v_add_u32_e32 v2, v4, v2
	v_cmp_ne_u32_e32 vcc, v3, v2
	s_and_saveexec_b64 s[6:7], vcc
	s_xor_b64 s[6:7], exec, s[6:7]
	s_cbranch_execz .LBB0_484
	s_waitcnt lgkmcnt(0)
	v_mov_b32_e32 v0, 0x2000
	global_load_dword v0, v0, s[4:5] offset:1024 sc1
	s_add_u32 s10, s4, 0x2400
	s_addc_u32 s11, s5, 0
	s_waitcnt vmcnt(0)
	v_cmp_eq_u32_e32 vcc, v0, v1
	s_and_saveexec_b64 s[8:9], vcc
	s_cbranch_execz .LBB0_483
	s_mov_b32 s3, 1
	s_mov_b64 s[12:13], 0
	v_mov_b32_e32 v0, 0
	s_branch .LBB0_474

; __device__ __forceinline__ unsigned xb_ld(unsigned* p)              { return __hip_atomic_load(p, __ATOMIC_RELAXED, __HIP_MEMORY_SCOPE_AGENT); }
; __device__ __forceinline__ unsigned xb_add(unsigned* p, unsigned v) { return __hip_atomic_fetch_add(p, v, __ATOMIC_RELAXED, __HIP_MEMORY_SCOPE_AGENT); }
; #define XB_SPIN(cond, bar) do { unsigned _sp = 0; while (cond) { __builtin_amdgcn_s_sleep(1); \
;     if ((++_sp & 255u) == 0u) { if (xb_ld(&(bar)[XB_TMO])) break; if (_sp > XB_SPIN_CAP) { atomicAdd(&(bar)[XB_TMO], 1u); break; } } } } while (0)
; __device__ __forceinline__ void xcd_barrier(const XcdBarrier& b) {
;     asm volatile("s_waitcnt vmcnt(0)" ::: "memory");
;     __syncthreads();
;     if (threadIdx.x == 0) {
;         unsigned* bar = b.bar;
;         __builtin_amdgcn_s_waitcnt(0);
;         unsigned nloc = b.st[0], nx = b.st[1];
;         if (nloc == 0u) { xcd_barrier_complete(bar, b.x, nloc, nx); b.st[0] = nloc; b.st[1] = nx; }
;         const unsigned old = xb_add(&bar[XB_XSUB(b.x)], 1u);
;         const unsigned gen = old / nloc;
;         if (old + 1u == (gen + 1u) * nloc) {
;             __builtin_amdgcn_fence(__ATOMIC_RELEASE, "agent");
;             asm volatile("s_waitcnt vmcnt(0)" ::: "memory");
;             const unsigned og = xb_add(&bar[XB_TOP], 1u);
;             const unsigned tg = og / nx;
;             if (og + 1u == (tg + 1u) * nx) xb_add(&bar[XB_TOPGEN], 1u);
;             else XB_SPIN(xb_ld(&bar[XB_TOPGEN]) == tg, bar);
;             __builtin_amdgcn_fence(__ATOMIC_ACQUIRE, "agent");
;             xb_add(&bar[XB_XGEN(b.x)], 1u);
;             asm volatile("s_waitcnt vmcnt(0)" ::: "memory");
;         } else {
;             XB_SPIN(xb_ld(&bar[XB_XGEN(b.x)]) == gen, bar);
.LBB0_687:
	s_mov_b64 s[6:7], exec
	v_readlane_b32 s3, v254, 19
	s_lshl_b32 s3, s3, 8
	v_mbcnt_lo_u32_b32 v1, s6, 0
	s_add_u32 s4, s58, s3
	v_mbcnt_hi_u32_b32 v1, s7, v1
	s_addc_u32 s5, s59, 0
	v_cmp_eq_u32_e32 vcc, 0, v1
	s_and_saveexec_b64 s[8:9], vcc
	s_cbranch_execz .LBB0_689
	s_bcnt1_i32_b64 s3, s[6:7]
	v_mov_b32_e32 v3, 0x1000
	v_mov_b32_e32 v4, s3
	global_atomic_add v3, v3, v4, s[4:5] offset:1024 sc0
	v_mov_b32_e32 v5, 0x3780
	global_load_dword v5, v5, s[58:59] sc0 sc1
.LBB0_689:
	s_or_b64 exec, exec, s[8:9]
	v_cvt_f32_u32_e32 v4, v2
	s_waitcnt vmcnt(0)
	v_readfirstlane_b32 s6, v5
	s_nop 1
	v_writelane_b32 v255, s6, 40
	v_readfirstlane_b32 s3, v3
	v_sub_u32_e32 v3, 0, v2
	v_rcp_iflag_f32_e32 v4, v4
	v_add_u32_e32 v5, s3, v1
	v_mul_f32_e32 v4, 0x4f7ffffe, v4
	v_cvt_u32_f32_e32 v4, v4
	v_mul_lo_u32 v1, v3, v4
	v_mul_hi_u32 v1, v4, v1
	v_add_u32_e32 v1, v4, v1
	v_mul_hi_u32 v1, v5, v1
	v_mul_lo_u32 v3, v1, v2
	v_sub_u32_e32 v3, v5, v3
	v_add_u32_e32 v4, 1, v1
	v_cmp_ge_u32_e32 vcc, v3, v2
	s_nop 1
	v_cndmask_b32_e32 v1, v1, v4, vcc
	v_sub_u32_e32 v4, v3, v2
	v_cndmask_b32_e32 v3, v3, v4, vcc
	v_add_u32_e32 v4, 1, v1
	v_cmp_ge_u32_e32 vcc, v3, v2
	v_add_u32_e32 v3, 1, v5
	s_nop 0
	v_cndmask_b32_e32 v1, v1, v4, vcc
	v_mul_lo_u32 v4, v2, v1
	v_add_u32_e32 v2, v4, v2
	v_cmp_ne_u32_e32 vcc, v3, v2
	s_and_saveexec_b64 s[6:7], vcc
	s_xor_b64 s[6:7], exec, s[6:7]
	s_cbranch_execz .LBB0_703
	s_waitcnt lgkmcnt(0)
	v_mov_b32_e32 v0, 0x2000
	global_load_dword v0, v0, s[4:5] offset:1024 sc1
	s_add_u32 s10, s4, 0x2400
	s_addc_u32 s11, s5, 0
	s_waitcnt vmcnt(0)
	v_cmp_eq_u32_e32 vcc, v0, v1
	s_and_saveexec_b64 s[8:9], vcc
	s_cbranch_execz .LBB0_702
	s_mov_b32 s3, 1
	s_mov_b64 s[12:13], 0
	v_mov_b32_e32 v0, 0
	s_branch .LBB0_693
